# XCD leaders poll the top-level arrival count itself (target from own arrival) instead of the generation word: one atomic hop less per grid barrier
# speedup vs baseline: 1.0002x; 1.0002x over previous
.LBB0_401:
	s_or_b64 exec, exec, s[20:21]
	s_waitcnt vmcnt(0)
	buffer_inv sc1
	v_readfirstlane_b32 s4, v4
	v_cvt_f32_u32_e32 v4, v2
	v_sub_u32_e32 v5, 0, v2
	v_add_u32_e32 v3, s4, v3
	v_readlane_b32 s4, v253, 44
	v_rcp_iflag_f32_e32 v4, v4
	v_readlane_b32 s5, v253, 45
	s_mov_b64 s[20:21], -1
	v_mul_f32_e32 v4, 0x4f7ffffe, v4
	v_cvt_u32_f32_e32 v4, v4
	v_mul_lo_u32 v5, v5, v4
	v_mul_hi_u32 v5, v4, v5
	v_add_u32_e32 v4, v4, v5
	v_mul_hi_u32 v4, v3, v4
	v_mul_lo_u32 v5, v4, v2
	v_sub_u32_e32 v5, v3, v5
	v_cmp_ge_u32_e32 vcc, v5, v2
	v_add_u32_e32 v6, 1, v4
	v_add_u32_e32 v3, 1, v3
	v_cndmask_b32_e32 v4, v4, v6, vcc
	v_sub_u32_e32 v6, v5, v2
	v_cndmask_b32_e32 v5, v5, v6, vcc
	v_cmp_ge_u32_e32 vcc, v5, v2
	v_add_u32_e32 v5, 1, v4
	s_nop 0
	v_cndmask_b32_e32 v4, v4, v5, vcc
	v_mul_lo_u32 v5, v2, v4
	v_add_u32_e32 v2, v5, v2
	v_cmp_ne_u32_e32 vcc, v3, v2
	v_mov_b32_e32 v4, v2
	v_mov_b64_e32 v[2:3], s[4:5]
	s_and_saveexec_b64 s[14:15], vcc
	s_cbranch_execz .LBB0_413
	v_readlane_b32 s4, v253, 42
	v_readlane_b32 s5, v253, 43
	s_mov_b64 s[30:31], 0
	s_nop 3
	global_load_dword v2, v99, s[4:5] sc1
	s_waitcnt vmcnt(0)
	v_cmp_lt_u32_e32 vcc, v2, v4
	s_and_saveexec_b64 s[20:21], vcc
	s_cbranch_execz .LBB0_412
	s_mov_b32 s18, 1
	s_branch .LBB0_405

.LBB0_407:
	v_readlane_b32 s4, v253, 42
	v_readlane_b32 s5, v253, 43
	s_add_i32 s18, s18, 1
	s_mov_b64 s[40:41], -1
	s_nop 2
	global_load_dword v2, v99, s[4:5] sc1
	s_waitcnt vmcnt(0)
	v_cmp_ge_u32_e32 vcc, v2, v4
	s_orn2_b64 s[38:39], vcc, exec
	s_branch .LBB0_404

.LBB0_540:
	s_or_b64 exec, exec, s[12:13]
	s_waitcnt vmcnt(0)
	buffer_inv sc1
	v_readfirstlane_b32 s4, v4
	v_cvt_f32_u32_e32 v4, v2
	v_sub_u32_e32 v5, 0, v2
	v_add_u32_e32 v3, s4, v3
	v_readlane_b32 s4, v253, 44
	v_rcp_iflag_f32_e32 v4, v4
	v_readlane_b32 s5, v253, 45
	s_mov_b64 s[12:13], -1
	v_mul_f32_e32 v4, 0x4f7ffffe, v4
	v_cvt_u32_f32_e32 v4, v4
	v_mul_lo_u32 v5, v5, v4
	v_mul_hi_u32 v5, v4, v5
	v_add_u32_e32 v4, v4, v5
	v_mul_hi_u32 v4, v3, v4
	v_mul_lo_u32 v5, v4, v2
	v_sub_u32_e32 v5, v3, v5
	v_cmp_ge_u32_e32 vcc, v5, v2
	v_add_u32_e32 v6, 1, v4
	v_add_u32_e32 v3, 1, v3
	v_cndmask_b32_e32 v4, v4, v6, vcc
	v_sub_u32_e32 v6, v5, v2
	v_cndmask_b32_e32 v5, v5, v6, vcc
	v_cmp_ge_u32_e32 vcc, v5, v2
	v_add_u32_e32 v5, 1, v4
	s_nop 0
	v_cndmask_b32_e32 v4, v4, v5, vcc
	v_mul_lo_u32 v5, v2, v4
	v_add_u32_e32 v2, v5, v2
	v_cmp_ne_u32_e32 vcc, v3, v2
	v_mov_b32_e32 v4, v2
	v_mov_b64_e32 v[2:3], s[4:5]
	s_and_saveexec_b64 s[10:11], vcc
	s_cbranch_execz .LBB0_552
	v_readlane_b32 s4, v253, 42
	v_readlane_b32 s5, v253, 43
	s_mov_b64 s[14:15], 0
	s_nop 3
	global_load_dword v2, v99, s[4:5] sc1
	s_waitcnt vmcnt(0)
	v_cmp_lt_u32_e32 vcc, v2, v4
	s_and_saveexec_b64 s[12:13], vcc
	s_cbranch_execz .LBB0_551
	s_mov_b32 s27, 1
	s_branch .LBB0_544

.LBB0_546:
	v_readlane_b32 s4, v253, 42
	v_readlane_b32 s5, v253, 43
	s_add_i32 s27, s27, 1
	s_mov_b64 s[38:39], -1
	s_nop 2
	global_load_dword v2, v99, s[4:5] sc1
	s_waitcnt vmcnt(0)
	v_cmp_ge_u32_e32 vcc, v2, v4
	s_orn2_b64 s[30:31], vcc, exec
	s_branch .LBB0_543

.LBB0_829:
	v_readlane_b32 s4, v253, 42
	v_readlane_b32 s5, v253, 43
	s_add_i32 s27, s27, 1
	s_mov_b64 s[36:37], -1
	s_nop 2
	global_load_dword v2, v99, s[4:5] sc1
	s_waitcnt vmcnt(0)
	v_cmp_ge_u32_e32 vcc, v2, v4
	s_orn2_b64 s[30:31], vcc, exec
	s_branch .LBB0_826

.LBB0_971:
	s_or_b64 exec, exec, s[14:15]
	s_waitcnt vmcnt(0)
	buffer_inv sc1
	v_readfirstlane_b32 s4, v4
	v_cvt_f32_u32_e32 v4, v2
	v_sub_u32_e32 v5, 0, v2
	v_add_u32_e32 v3, s4, v3
	v_readlane_b32 s4, v253, 44
	v_rcp_iflag_f32_e32 v4, v4
	v_readlane_b32 s5, v253, 45
	s_mov_b64 s[14:15], -1
	v_mul_f32_e32 v4, 0x4f7ffffe, v4
	v_cvt_u32_f32_e32 v4, v4
	v_mul_lo_u32 v5, v5, v4
	v_mul_hi_u32 v5, v4, v5
	v_add_u32_e32 v4, v4, v5
	v_mul_hi_u32 v4, v3, v4
	v_mul_lo_u32 v5, v4, v2
	v_sub_u32_e32 v5, v3, v5
	v_cmp_ge_u32_e32 vcc, v5, v2
	v_add_u32_e32 v6, 1, v4
	v_add_u32_e32 v3, 1, v3
	v_cndmask_b32_e32 v4, v4, v6, vcc
	v_sub_u32_e32 v6, v5, v2
	v_cndmask_b32_e32 v5, v5, v6, vcc
	v_cmp_ge_u32_e32 vcc, v5, v2
	v_add_u32_e32 v5, 1, v4
	s_nop 0
	v_cndmask_b32_e32 v4, v4, v5, vcc
	v_mul_lo_u32 v5, v2, v4
	v_add_u32_e32 v2, v5, v2
	v_cmp_ne_u32_e32 vcc, v3, v2
	v_mov_b32_e32 v4, v2
	v_mov_b64_e32 v[2:3], s[4:5]
	s_and_saveexec_b64 s[12:13], vcc
	s_cbranch_execz .LBB0_983
	v_readlane_b32 s4, v253, 42
	v_readlane_b32 s5, v253, 43
	s_mov_b64 s[20:21], 0
	s_nop 3
	global_load_dword v2, v99, s[4:5] sc1
	s_waitcnt vmcnt(0)
	v_cmp_lt_u32_e32 vcc, v2, v4
	s_and_saveexec_b64 s[14:15], vcc
	s_cbranch_execz .LBB0_982
	s_mov_b32 s27, 1
	s_branch .LBB0_975

.LBB0_977:
	v_readlane_b32 s4, v253, 42
	v_readlane_b32 s5, v253, 43
	s_add_i32 s27, s27, 1
	s_mov_b64 s[38:39], -1
	s_nop 2
	global_load_dword v2, v99, s[4:5] sc1
	s_waitcnt vmcnt(0)
	v_cmp_ge_u32_e32 vcc, v2, v4
	s_orn2_b64 s[36:37], vcc, exec
	s_branch .LBB0_974

.LBB0_1267:
	s_or_b64 exec, exec, s[20:21]
	s_waitcnt vmcnt(0)
	buffer_inv sc1
	v_readfirstlane_b32 s4, v4
	v_cvt_f32_u32_e32 v4, v2
	v_sub_u32_e32 v5, 0, v2
	v_add_u32_e32 v3, s4, v3
	v_readlane_b32 s4, v253, 44
	v_rcp_iflag_f32_e32 v4, v4
	v_readlane_b32 s5, v253, 45
	s_mov_b64 s[20:21], -1
	v_mul_f32_e32 v4, 0x4f7ffffe, v4
	v_cvt_u32_f32_e32 v4, v4
	v_mul_lo_u32 v5, v5, v4
	v_mul_hi_u32 v5, v4, v5
	v_add_u32_e32 v4, v4, v5
	v_mul_hi_u32 v4, v3, v4
	v_mul_lo_u32 v5, v4, v2
	v_sub_u32_e32 v5, v3, v5
	v_cmp_ge_u32_e32 vcc, v5, v2
	v_add_u32_e32 v6, 1, v4
	v_add_u32_e32 v3, 1, v3
	v_cndmask_b32_e32 v4, v4, v6, vcc
	v_sub_u32_e32 v6, v5, v2
	v_cndmask_b32_e32 v5, v5, v6, vcc
	v_cmp_ge_u32_e32 vcc, v5, v2
	v_add_u32_e32 v5, 1, v4
	s_nop 0
	v_cndmask_b32_e32 v4, v4, v5, vcc
	v_mul_lo_u32 v5, v2, v4
	v_add_u32_e32 v2, v5, v2
	v_cmp_ne_u32_e32 vcc, v3, v2
	v_mov_b32_e32 v4, v2
	v_mov_b64_e32 v[2:3], s[4:5]
	s_and_saveexec_b64 s[14:15], vcc
	s_cbranch_execz .LBB0_1296
	v_readlane_b32 s4, v253, 42
	v_readlane_b32 s5, v253, 43
	s_mov_b64 s[26:27], 0
	s_nop 3
	global_load_dword v2, v99, s[4:5] sc1
	s_waitcnt vmcnt(0)
	v_cmp_lt_u32_e32 vcc, v2, v4
	s_and_saveexec_b64 s[20:21], vcc
	s_cbranch_execz .LBB0_1295
	s_mov_b32 s18, 1
	s_branch .LBB0_1271

.LBB0_1273:
	v_readlane_b32 s4, v253, 42
	v_readlane_b32 s5, v253, 43
	s_add_i32 s18, s18, 1
	s_mov_b64 s[38:39], -1
	s_nop 2
	global_load_dword v2, v99, s[4:5] sc1
	s_waitcnt vmcnt(0)
	v_cmp_ge_u32_e32 vcc, v2, v4
	s_orn2_b64 s[36:37], vcc, exec
	s_branch .LBB0_1270

.LBB0_1284:
	s_or_b64 exec, exec, s[12:13]
	s_waitcnt vmcnt(0)
	buffer_inv sc1
	v_readfirstlane_b32 s4, v4
	v_cvt_f32_u32_e32 v4, v2
	v_sub_u32_e32 v5, 0, v2
	v_add_u32_e32 v3, s4, v3
	v_readlane_b32 s4, v253, 44
	v_rcp_iflag_f32_e32 v4, v4
	v_readlane_b32 s5, v253, 45
	s_mov_b64 s[12:13], -1
	v_mul_f32_e32 v4, 0x4f7ffffe, v4
	v_cvt_u32_f32_e32 v4, v4
	v_mul_lo_u32 v5, v5, v4
	v_mul_hi_u32 v5, v4, v5
	v_add_u32_e32 v4, v4, v5
	v_mul_hi_u32 v4, v3, v4
	v_mul_lo_u32 v5, v4, v2
	v_sub_u32_e32 v5, v3, v5
	v_cmp_ge_u32_e32 vcc, v5, v2
	v_add_u32_e32 v6, 1, v4
	v_add_u32_e32 v3, 1, v3
	v_cndmask_b32_e32 v4, v4, v6, vcc
	v_sub_u32_e32 v6, v5, v2
	v_cndmask_b32_e32 v5, v5, v6, vcc
	v_cmp_ge_u32_e32 vcc, v5, v2
	v_add_u32_e32 v5, 1, v4
	s_nop 0
	v_cndmask_b32_e32 v4, v4, v5, vcc
	v_mul_lo_u32 v5, v2, v4
	v_add_u32_e32 v2, v5, v2
	v_cmp_ne_u32_e32 vcc, v3, v2
	v_mov_b32_e32 v4, v2
	v_mov_b64_e32 v[2:3], s[4:5]
	s_and_saveexec_b64 s[10:11], vcc
	s_cbranch_execz .LBB0_1304
	v_readlane_b32 s4, v253, 42
	v_readlane_b32 s5, v253, 43
	s_mov_b64 s[14:15], 0
	s_nop 3
	global_load_dword v2, v99, s[4:5] sc1
	s_waitcnt vmcnt(0)
	v_cmp_lt_u32_e32 vcc, v2, v4
	s_and_saveexec_b64 s[12:13], vcc
	s_cbranch_execz .LBB0_1303
	s_mov_b32 s18, 1
	s_branch .LBB0_1288

.LBB0_1290:
	v_readlane_b32 s4, v253, 42
	v_readlane_b32 s5, v253, 43
	s_add_i32 s18, s18, 1
	s_mov_b64 s[30:31], -1
	s_nop 2
	global_load_dword v2, v99, s[4:5] sc1
	s_waitcnt vmcnt(0)
	v_cmp_ge_u32_e32 vcc, v2, v4
	s_orn2_b64 s[26:27], vcc, exec
	s_branch .LBB0_1287
